# diff attention: cross-half row-max combine (permlane32 swap) moved to the rare rescale path; common path tests per-lane max directly
# speedup vs baseline: 1.0061x; 1.0025x over previous
; __device__ __forceinline__ float rowmax32(const f32x16& a, const f32x16& b) {
;     float m0 = fmaxf(a[0], b[0]), m1 = fmaxf(a[1], b[1]);
; #pragma unroll
;     for (int r = 2; r < 16; r += 2) { m0 = fmaxf(m0, fmaxf(a[r], b[r])); m1 = fmaxf(m1, fmaxf(a[r + 1], b[r + 1])); }
;     const float m = fmaxf(m0, m1);
;     auto rr = __builtin_amdgcn_permlane32_swap(__float_as_uint(m), __float_as_uint(m), false, false);
;     return fmaxf(__uint_as_float(rr[0]), __uint_as_float(rr[1]));
; }
; template <bool HAS_QK, bool HAS_PV> ...
;     ...
;         const float rm = rowmax32(s0, s1);
;         need = first || __any(rm > 8.f);
;         if (need) { const float dl = first ? rm : fmaxf(rm, 0.f); mrun += dl; f = first ? 1.f : __builtin_amdgcn_exp2f(-dl);
; #pragma unroll
;             for (int r = 0; r < 16; ++r) { s0[r] -= dl; s1[r] -= dl; } }
.LBB0_209:
	v_max_f32_e32 v0, v128, v80
	v_max_f32_e32 v4, v129, v81
	v_max3_f32 v0, v0, v130, v82
	v_max3_f32 v4, v4, v131, v83
	v_max3_f32 v0, v0, v132, v84
	v_max3_f32 v4, v4, v133, v85
	v_max3_f32 v0, v0, v134, v86
	v_max3_f32 v4, v4, v135, v87
	v_max3_f32 v0, v0, v136, v88
	v_max3_f32 v4, v4, v137, v89
	v_max3_f32 v0, v0, v138, v90
	v_max3_f32 v4, v4, v139, v91
	v_max3_f32 v0, v0, v140, v92
	v_max3_f32 v4, v4, v141, v93
	v_max3_f32 v0, v0, v142, v94
	v_max3_f32 v4, v4, v143, v95
	v_max_f32_e32 v0, v0, v4
	s_cmp_lg_u32 s29, 0
	s_cselect_b64 s[4:5], -1, 0
	s_cmp_eq_u32 s29, 0
	s_cbranch_scc1 .Ldiff_combine_a
	v_cmp_lt_f32_e32 vcc, s86, v0
	s_cmp_lg_u64 vcc, 0
	s_cselect_b64 s[10:11], -1, 0
	s_cbranch_scc1 .Ldiff_combine_a
	v_mov_b32_e32 v0, 1.0
	s_branch .LBB0_212
.Ldiff_combine_a:
	v_mov_b32_e32 v4, v0
	s_nop 1
	v_permlane32_swap_b32_e32 v0, v4
	v_max_f32_e32 v4, v0, v4
	s_cmp_eq_u32 s29, 0
	s_cbranch_scc1 .LBB0_217
	s_mov_b64 s[10:11], -1

; template <bool HAS_QK, bool HAS_PV> ...
;     ...
;         const float rm = rowmax32(s0, s1);
;         need = first || __any(rm > 8.f);
;         if (need) { const float dl = first ? rm : fmaxf(rm, 0.f); mrun += dl; f = first ? 1.f : __builtin_amdgcn_exp2f(-dl);
; #pragma unroll
;             for (int r = 0; r < 16; ++r) { s0[r] -= dl; s1[r] -= dl; } }
.LBB0_222:
	s_nop 10
	v_max_f32_e32 v2, v112, v96
	v_max_f32_e32 v3, v113, v97
	v_max3_f32 v2, v2, v114, v98
	v_max3_f32 v3, v3, v115, v99
	v_max3_f32 v2, v2, v116, v100
	v_max3_f32 v3, v3, v117, v101
	v_max3_f32 v2, v2, v118, v102
	v_max3_f32 v3, v3, v119, v103
	v_max3_f32 v2, v2, v120, v104
	v_max3_f32 v3, v3, v121, v105
	v_max3_f32 v2, v2, v122, v106
	v_max3_f32 v3, v3, v123, v107
	v_max3_f32 v2, v2, v124, v108
	v_max3_f32 v3, v3, v125, v109
	v_max3_f32 v2, v2, v126, v110
	v_max3_f32 v3, v3, v127, v111
	v_max_f32_e32 v2, v2, v3
	v_cmp_lt_f32_e32 vcc, s86, v2
	s_cmp_lg_u64 vcc, 0
	s_cselect_b64 s[4:5], -1, 0
	s_cbranch_vccz .LBB0_224
	v_mov_b32_e32 v3, v2
	s_nop 1
	v_permlane32_swap_b32_e32 v2, v3
	v_max_f32_e32 v2, v2, v3
	v_max_f32_e32 v2, v2, v2
	v_max_f32_e32 v2, 0, v2
	v_exp_f32_e64 v14, -v2
	v_add_f32_e32 v15, v15, v2
	v_pk_add_f32 v[112:113], v[112:113], v[2:3] op_sel_hi:[1,0] neg_lo:[0,1] neg_hi:[0,1]
	v_pk_add_f32 v[96:97], v[96:97], v[2:3] op_sel_hi:[1,0] neg_lo:[0,1] neg_hi:[0,1]
	v_pk_add_f32 v[114:115], v[114:115], v[2:3] op_sel_hi:[1,0] neg_lo:[0,1] neg_hi:[0,1]
	v_pk_add_f32 v[98:99], v[98:99], v[2:3] op_sel_hi:[1,0] neg_lo:[0,1] neg_hi:[0,1]
	v_pk_add_f32 v[116:117], v[116:117], v[2:3] op_sel_hi:[1,0] neg_lo:[0,1] neg_hi:[0,1]
	v_pk_add_f32 v[100:101], v[100:101], v[2:3] op_sel_hi:[1,0] neg_lo:[0,1] neg_hi:[0,1]
	v_pk_add_f32 v[118:119], v[118:119], v[2:3] op_sel_hi:[1,0] neg_lo:[0,1] neg_hi:[0,1]
	v_pk_add_f32 v[102:103], v[102:103], v[2:3] op_sel_hi:[1,0] neg_lo:[0,1] neg_hi:[0,1]
	v_pk_add_f32 v[120:121], v[120:121], v[2:3] op_sel_hi:[1,0] neg_lo:[0,1] neg_hi:[0,1]
	v_pk_add_f32 v[104:105], v[104:105], v[2:3] op_sel_hi:[1,0] neg_lo:[0,1] neg_hi:[0,1]
	v_pk_add_f32 v[122:123], v[122:123], v[2:3] op_sel_hi:[1,0] neg_lo:[0,1] neg_hi:[0,1]
	v_pk_add_f32 v[106:107], v[106:107], v[2:3] op_sel_hi:[1,0] neg_lo:[0,1] neg_hi:[0,1]
	v_pk_add_f32 v[124:125], v[124:125], v[2:3] op_sel_hi:[1,0] neg_lo:[0,1] neg_hi:[0,1]
	v_pk_add_f32 v[108:109], v[108:109], v[2:3] op_sel_hi:[1,0] neg_lo:[0,1] neg_hi:[0,1]
	v_pk_add_f32 v[126:127], v[126:127], v[2:3] op_sel_hi:[1,0] neg_lo:[0,1] neg_hi:[0,1]
	v_pk_add_f32 v[110:111], v[110:111], v[2:3] op_sel_hi:[1,0] neg_lo:[0,1] neg_hi:[0,1]
	s_branch .LBB0_225
